# P3 start stagger of the 4-tile CU groups widened to 20/40/60 us
# baseline (speedup 1.0000x reference)
; #define SEAM(k) do { if (IN(k) && IN((k) + 1)) { if (a.ph_hi > 4096) cg::this_grid().sync(); else xcd_barrier(xbar); } } while (0)
; __global__ void __launch_bounds__(512, 2) fwd_kernel(Args a) {
;     ...
;     if (IN(2)) { pg8::Gemm g{XN, (const bf16_t*)(ws + WS_W1A), MALL, NFF2, D}; pg8::StaticOrder S; S.init(MALL, NFF2, G, (int)blockIdx.x); EpiSwiGLU<false> E{ZH, nullptr, nullptr};
;         pg8::gemm_phase<EpiSwiGLU<false>, pg8::StaticOrder, true, true>(ldsg, g, S, E); } SEAM(2);
;     if (IN(3)) { pg8::Gemm g{ZH, (const bf16_t*)(ws + WS_W1B), MALL, D, DFF}; pg8::StaticOrder S; S.init(MALL, D, G, (int)blockIdx.x); typedef EpiResid<2, true, true, 4> EpiT; EpiT E{a.in[I_X], a.in[I_CTX], a.out, X1C, mod, XN, a.in[I_N2G], (float*)(ws + WS_RS2)};
;         pg8::gemm_phase<EpiT, pg8::StaticOrder, true, true>(ldsg, g, S, E); } SEAM(3);
.LBB0_363:
	s_lshr_b32 s100, s2, 6
	s_and_b32 s100, s100, 3
	s_mul_i32 s100, s100, 2000
	s_memrealtime s[98:99]
	s_waitcnt lgkmcnt(0)
	s_add_u32 s100, s100, s98
